# adds: W1 activation epilogue regenerated with the lane-pair exchange (128-byte store pieces); silu(c) staging loads issued together; HGRN2 state-fold loads issued together
# speedup vs baseline: 1.0371x; 1.0055x over previous
.LBB0_11:
	s_load_dwordx16 s[12:27], s[0:1], 0x0
	s_and_b32 s2, s33, 0xffffffc0
	v_mbcnt_lo_u32_b32 v4, -1, 0
	v_mbcnt_hi_u32_b32 v4, -1, v4
	s_movk_i32 s3, 0x2000
	v_add_u32_e32 v10, s2, v4
	s_waitcnt lgkmcnt(0)
	v_writelane_b32 v246, s12, 7
	v_cmp_gt_i32_e32 vcc, s3, v10
	s_nop 0
	v_writelane_b32 v246, s13, 8
	v_writelane_b32 v246, s14, 9
	v_writelane_b32 v246, s15, 10
	v_writelane_b32 v246, s16, 11
	v_writelane_b32 v246, s17, 12
	v_writelane_b32 v246, s18, 13
	v_writelane_b32 v246, s19, 14
	v_writelane_b32 v246, s20, 15
	v_writelane_b32 v246, s21, 16
	v_writelane_b32 v246, s22, 17
	v_writelane_b32 v246, s23, 18
	v_writelane_b32 v246, s24, 19
	v_writelane_b32 v246, s25, 20
	v_writelane_b32 v246, s26, 21
	v_writelane_b32 v246, s27, 22
	v_writelane_b32 v246, s2, 23
	s_and_saveexec_b64 s[4:5], vcc
	s_cbranch_execz .LBB0_14
	s_load_dwordx16 s[12:27], s[0:1], 0x0
	s_lshl_b32 s3, s33, 3
	s_and_b32 s3, s3, 0xfffffe00
	v_ashrrev_i32_e32 v11, 31, v10
	v_lshl_add_u32 v5, v4, 3, s3
	s_waitcnt lgkmcnt(0)
	v_mov_b32_e32 v2, s14
	v_mov_b32_e32 v3, s15
	v_lshl_add_u64 v[2:3], v[10:11], 2, v[2:3]
	s_mov_b64 s[6:7], 0
	s_mov_b64 s[10:11], 0x800
	s_movk_i32 s3, 0x1dff
	v_mov_b32_e32 v6, v10
	v_lshlrev_b32_e32 v200, 2, v10
	s_mov_b64 s[98:99], s[14:15]
	global_load_dword v201, v200, s[98:99]
	s_add_u32 s98, s98, 0x800
	s_addc_u32 s99, s99, 0
	global_load_dword v202, v200, s[98:99]
	s_add_u32 s98, s98, 0x800
	s_addc_u32 s99, s99, 0
	global_load_dword v203, v200, s[98:99]
	s_add_u32 s98, s98, 0x800
	s_addc_u32 s99, s99, 0
	global_load_dword v204, v200, s[98:99]
	s_add_u32 s98, s98, 0x800
	s_addc_u32 s99, s99, 0
	global_load_dword v205, v200, s[98:99]
	s_add_u32 s98, s98, 0x800
	s_addc_u32 s99, s99, 0
	global_load_dword v206, v200, s[98:99]
	s_add_u32 s98, s98, 0x800
	s_addc_u32 s99, s99, 0
	global_load_dword v207, v200, s[98:99]
	s_add_u32 s98, s98, 0x800
	s_addc_u32 s99, s99, 0
	global_load_dword v208, v200, s[98:99]
	s_add_u32 s98, s98, 0x800
	s_addc_u32 s99, s99, 0
	global_load_dword v209, v200, s[98:99]
	s_add_u32 s98, s98, 0x800
	s_addc_u32 s99, s99, 0
	global_load_dword v210, v200, s[98:99]
	s_add_u32 s98, s98, 0x800
	s_addc_u32 s99, s99, 0
	global_load_dword v211, v200, s[98:99]
	s_add_u32 s98, s98, 0x800
	s_addc_u32 s99, s99, 0
	global_load_dword v212, v200, s[98:99]
	s_add_u32 s98, s98, 0x800
	s_addc_u32 s99, s99, 0
	global_load_dword v213, v200, s[98:99]
	s_add_u32 s98, s98, 0x800
	s_addc_u32 s99, s99, 0
	global_load_dword v214, v200, s[98:99]
	s_add_u32 s98, s98, 0x800
	s_addc_u32 s99, s99, 0
	global_load_dword v215, v200, s[98:99]
	v_add_u32_e32 v217, 0, v10
	v_lshlrev_b32_e32 v218, 3, v217
	v_and_b32_e32 v218, 0x1ff8, v218
	v_lshlrev_b32_e32 v218, 2, v218
	v_ashrrev_i32_e32 v217, 10, v217
	v_lshlrev_b32_e32 v217, 2, v217
	v_add3_u32 v217, 0, v218, v217
	s_waitcnt vmcnt(14)
	v_mul_f32_e32 v216, 0xbfb8aa3b, v201
	v_exp_f32_e32 v216, v216
	s_nop 0
	v_add_f32_e32 v219, 1.0, v216
	v_rcp_f32_e32 v216, v219
	s_nop 0
	v_mul_f32_e32 v201, v201, v216
	ds_write_b32 v217, v201
	v_add_u32_e32 v217, 512, v10
	v_lshlrev_b32_e32 v218, 3, v217
	v_and_b32_e32 v218, 0x1ff8, v218
	v_lshlrev_b32_e32 v218, 2, v218
	v_ashrrev_i32_e32 v217, 10, v217
	v_lshlrev_b32_e32 v217, 2, v217
	v_add3_u32 v217, 0, v218, v217
	s_waitcnt vmcnt(13)
	v_mul_f32_e32 v216, 0xbfb8aa3b, v202
	v_exp_f32_e32 v216, v216
	s_nop 0
	v_add_f32_e32 v219, 1.0, v216
	v_rcp_f32_e32 v216, v219
	s_nop 0
	v_mul_f32_e32 v202, v202, v216
	ds_write_b32 v217, v202
	v_add_u32_e32 v217, 1024, v10
	v_lshlrev_b32_e32 v218, 3, v217
	v_and_b32_e32 v218, 0x1ff8, v218
	v_lshlrev_b32_e32 v218, 2, v218
	v_ashrrev_i32_e32 v217, 10, v217
	v_lshlrev_b32_e32 v217, 2, v217
	v_add3_u32 v217, 0, v218, v217
	s_waitcnt vmcnt(12)
	v_mul_f32_e32 v216, 0xbfb8aa3b, v203
	v_exp_f32_e32 v216, v216
	s_nop 0
	v_add_f32_e32 v219, 1.0, v216
	v_rcp_f32_e32 v216, v219
	s_nop 0
	v_mul_f32_e32 v203, v203, v216
	ds_write_b32 v217, v203
	v_add_u32_e32 v217, 1536, v10
	v_lshlrev_b32_e32 v218, 3, v217
	v_and_b32_e32 v218, 0x1ff8, v218
	v_lshlrev_b32_e32 v218, 2, v218
	v_ashrrev_i32_e32 v217, 10, v217
	v_lshlrev_b32_e32 v217, 2, v217
	v_add3_u32 v217, 0, v218, v217
	s_waitcnt vmcnt(11)
	v_mul_f32_e32 v216, 0xbfb8aa3b, v204
	v_exp_f32_e32 v216, v216
	s_nop 0
	v_add_f32_e32 v219, 1.0, v216
	v_rcp_f32_e32 v216, v219
	s_nop 0
	v_mul_f32_e32 v204, v204, v216
	ds_write_b32 v217, v204
	v_add_u32_e32 v217, 2048, v10
	v_lshlrev_b32_e32 v218, 3, v217
	v_and_b32_e32 v218, 0x1ff8, v218
	v_lshlrev_b32_e32 v218, 2, v218
	v_ashrrev_i32_e32 v217, 10, v217
	v_lshlrev_b32_e32 v217, 2, v217
	v_add3_u32 v217, 0, v218, v217
	s_waitcnt vmcnt(10)
	v_mul_f32_e32 v216, 0xbfb8aa3b, v205
	v_exp_f32_e32 v216, v216
	s_nop 0
	v_add_f32_e32 v219, 1.0, v216
	v_rcp_f32_e32 v216, v219
	s_nop 0
	v_mul_f32_e32 v205, v205, v216
	ds_write_b32 v217, v205
	v_add_u32_e32 v217, 2560, v10
	v_lshlrev_b32_e32 v218, 3, v217
	v_and_b32_e32 v218, 0x1ff8, v218
	v_lshlrev_b32_e32 v218, 2, v218
	v_ashrrev_i32_e32 v217, 10, v217
	v_lshlrev_b32_e32 v217, 2, v217
	v_add3_u32 v217, 0, v218, v217
	s_waitcnt vmcnt(9)
	v_mul_f32_e32 v216, 0xbfb8aa3b, v206
	v_exp_f32_e32 v216, v216
	s_nop 0
	v_add_f32_e32 v219, 1.0, v216
	v_rcp_f32_e32 v216, v219
	s_nop 0
	v_mul_f32_e32 v206, v206, v216
	ds_write_b32 v217, v206
	v_add_u32_e32 v217, 3072, v10
	v_lshlrev_b32_e32 v218, 3, v217
	v_and_b32_e32 v218, 0x1ff8, v218
	v_lshlrev_b32_e32 v218, 2, v218
	v_ashrrev_i32_e32 v217, 10, v217
	v_lshlrev_b32_e32 v217, 2, v217
	v_add3_u32 v217, 0, v218, v217
	s_waitcnt vmcnt(8)
	v_mul_f32_e32 v216, 0xbfb8aa3b, v207
	v_exp_f32_e32 v216, v216
	s_nop 0
	v_add_f32_e32 v219, 1.0, v216
	v_rcp_f32_e32 v216, v219
	s_nop 0
	v_mul_f32_e32 v207, v207, v216
	ds_write_b32 v217, v207
	v_add_u32_e32 v217, 3584, v10
	v_lshlrev_b32_e32 v218, 3, v217
	v_and_b32_e32 v218, 0x1ff8, v218
	v_lshlrev_b32_e32 v218, 2, v218
	v_ashrrev_i32_e32 v217, 10, v217
	v_lshlrev_b32_e32 v217, 2, v217
	v_add3_u32 v217, 0, v218, v217
	s_waitcnt vmcnt(7)
	v_mul_f32_e32 v216, 0xbfb8aa3b, v208
	v_exp_f32_e32 v216, v216
	s_nop 0
	v_add_f32_e32 v219, 1.0, v216
	v_rcp_f32_e32 v216, v219
	s_nop 0
	v_mul_f32_e32 v208, v208, v216
	ds_write_b32 v217, v208
	v_add_u32_e32 v217, 4096, v10
	v_lshlrev_b32_e32 v218, 3, v217
	v_and_b32_e32 v218, 0x1ff8, v218
	v_lshlrev_b32_e32 v218, 2, v218
	v_ashrrev_i32_e32 v217, 10, v217
	v_lshlrev_b32_e32 v217, 2, v217
	v_add3_u32 v217, 0, v218, v217
	s_waitcnt vmcnt(6)
	v_mul_f32_e32 v216, 0xbfb8aa3b, v209
	v_exp_f32_e32 v216, v216
	s_nop 0
	v_add_f32_e32 v219, 1.0, v216
	v_rcp_f32_e32 v216, v219
	s_nop 0
	v_mul_f32_e32 v209, v209, v216
	ds_write_b32 v217, v209
	v_add_u32_e32 v217, 4608, v10
	v_lshlrev_b32_e32 v218, 3, v217
	v_and_b32_e32 v218, 0x1ff8, v218
	v_lshlrev_b32_e32 v218, 2, v218
	v_ashrrev_i32_e32 v217, 10, v217
	v_lshlrev_b32_e32 v217, 2, v217
	v_add3_u32 v217, 0, v218, v217
	s_waitcnt vmcnt(5)
	v_mul_f32_e32 v216, 0xbfb8aa3b, v210
	v_exp_f32_e32 v216, v216
	s_nop 0
	v_add_f32_e32 v219, 1.0, v216
	v_rcp_f32_e32 v216, v219
	s_nop 0
	v_mul_f32_e32 v210, v210, v216
	ds_write_b32 v217, v210
	v_add_u32_e32 v217, 5120, v10
	v_lshlrev_b32_e32 v218, 3, v217
	v_and_b32_e32 v218, 0x1ff8, v218
	v_lshlrev_b32_e32 v218, 2, v218
	v_ashrrev_i32_e32 v217, 10, v217
	v_lshlrev_b32_e32 v217, 2, v217
	v_add3_u32 v217, 0, v218, v217
	s_waitcnt vmcnt(4)
	v_mul_f32_e32 v216, 0xbfb8aa3b, v211
	v_exp_f32_e32 v216, v216
	s_nop 0
	v_add_f32_e32 v219, 1.0, v216
	v_rcp_f32_e32 v216, v219
	s_nop 0
	v_mul_f32_e32 v211, v211, v216
	ds_write_b32 v217, v211
	v_add_u32_e32 v217, 5632, v10
	v_lshlrev_b32_e32 v218, 3, v217
	v_and_b32_e32 v218, 0x1ff8, v218
	v_lshlrev_b32_e32 v218, 2, v218
	v_ashrrev_i32_e32 v217, 10, v217
	v_lshlrev_b32_e32 v217, 2, v217
	v_add3_u32 v217, 0, v218, v217
	s_waitcnt vmcnt(3)
	v_mul_f32_e32 v216, 0xbfb8aa3b, v212
	v_exp_f32_e32 v216, v216
	s_nop 0
	v_add_f32_e32 v219, 1.0, v216
	v_rcp_f32_e32 v216, v219
	s_nop 0
	v_mul_f32_e32 v212, v212, v216
	ds_write_b32 v217, v212
	v_add_u32_e32 v217, 6144, v10
	v_lshlrev_b32_e32 v218, 3, v217
	v_and_b32_e32 v218, 0x1ff8, v218
	v_lshlrev_b32_e32 v218, 2, v218
	v_ashrrev_i32_e32 v217, 10, v217
	v_lshlrev_b32_e32 v217, 2, v217
	v_add3_u32 v217, 0, v218, v217
	s_waitcnt vmcnt(2)
	v_mul_f32_e32 v216, 0xbfb8aa3b, v213
	v_exp_f32_e32 v216, v216
	s_nop 0
	v_add_f32_e32 v219, 1.0, v216
	v_rcp_f32_e32 v216, v219
	s_nop 0
	v_mul_f32_e32 v213, v213, v216
	ds_write_b32 v217, v213
	v_add_u32_e32 v217, 6656, v10
	v_lshlrev_b32_e32 v218, 3, v217
	v_and_b32_e32 v218, 0x1ff8, v218
	v_lshlrev_b32_e32 v218, 2, v218
	v_ashrrev_i32_e32 v217, 10, v217
	v_lshlrev_b32_e32 v217, 2, v217
	v_add3_u32 v217, 0, v218, v217
	s_waitcnt vmcnt(1)
	v_mul_f32_e32 v216, 0xbfb8aa3b, v214
	v_exp_f32_e32 v216, v216
	s_nop 0
	v_add_f32_e32 v219, 1.0, v216
	v_rcp_f32_e32 v216, v219
	s_nop 0
	v_mul_f32_e32 v214, v214, v216
	ds_write_b32 v217, v214
	v_add_u32_e32 v217, 7168, v10
	v_lshlrev_b32_e32 v218, 3, v217
	v_and_b32_e32 v218, 0x1ff8, v218
	v_lshlrev_b32_e32 v218, 2, v218
	v_ashrrev_i32_e32 v217, 10, v217
	v_lshlrev_b32_e32 v217, 2, v217
	v_add3_u32 v217, 0, v218, v217
	s_waitcnt vmcnt(0)
	v_mul_f32_e32 v216, 0xbfb8aa3b, v215
	v_exp_f32_e32 v216, v216
	s_nop 0
	v_add_f32_e32 v219, 1.0, v216
	v_rcp_f32_e32 v216, v219
	s_nop 0
	v_mul_f32_e32 v215, v215, v216
	ds_write_b32 v217, v215
	v_add_co_u32_e32 v2, vcc, 0x7800, v2
	s_nop 1
	v_addc_co_u32_e32 v3, vcc, 0, v3, vcc
	v_add_u32_e32 v5, 0xf000, v5
	v_add_u32_e32 v6, 0x1e00, v6

.LBB0_1394:
	s_lshl_b32 s26, s52, 11
	s_add_i32 s26, s26, 0x20400
	s_lshl_b32 s27, s40, 2
	s_add_i32 s27, s26, s27
	v_lshl_add_u32 v130, v180, 2, s27
	ds_read_b32 v133, v130 offset:0
	ds_read_b32 v134, v130 offset:64
	ds_read_b32 v135, v130 offset:128
	ds_read_b32 v136, v130 offset:192
	ds_read_b32 v137, v130 offset:512
	ds_read_b32 v138, v130 offset:576
	ds_read_b32 v139, v130 offset:640
	ds_read_b32 v140, v130 offset:704
	s_lshl_b32 s27, s41, 2
	s_add_i32 s27, s26, s27
	v_lshl_add_u32 v130, v182, 2, s27
	ds_read_b128 v[142:145], v130 offset:1024
	ds_read_b128 v[168:171], v130 offset:1040
	ds_read_b128 v[172:175], v130 offset:1536
	ds_read_b128 v[176:179], v130 offset:1552
	s_mov_b32 s62, 0xaaaaaaaa
	s_mov_b32 s63, 0xaaaaaaaa
	s_mov_b32 s66, 0x55555555
	s_mov_b32 s67, 0x55555555
	v_and_b32_e32 v132, 1, v180
	v_lshl_or_b32 v131, s41, 1, v182
	v_lshl_or_b32 v131, s48, 8, v131
	v_lshl_add_u32 v131, v132, 5, v131
	v_lshl_add_u32 v130, s49, 8, v181
	v_sub_u32_e32 v130, v130, v132
	v_lshlrev_b32_e32 v130, 13, v130
	v_lshl_add_u32 v131, v131, 1, v130
	s_waitcnt lgkmcnt(0)
	v_fma_f32 v126, v126, v133, v142
	v_fma_f32 v127, v127, v133, v143
	v_fma_f32 v128, v128, v133, v144
	v_fma_f32 v129, v129, v133, v145
	v_fma_f32 v122, v122, v133, v168
	v_fma_f32 v123, v123, v133, v169
	v_fma_f32 v124, v124, v133, v170
	v_fma_f32 v125, v125, v133, v171
	v_max_f32_e32 v126, 0, v126
	v_max_f32_e32 v127, 0, v127
	v_max_f32_e32 v128, 0, v128
	v_max_f32_e32 v129, 0, v129
	v_max_f32_e32 v122, 0, v122
	v_max_f32_e32 v123, 0, v123
	v_max_f32_e32 v124, 0, v124
	v_max_f32_e32 v125, 0, v125
	v_pk_mul_f32 v[126:127], v[126:127], v[126:127]
	v_pk_mul_f32 v[128:129], v[128:129], v[128:129]
	v_pk_mul_f32 v[122:123], v[122:123], v[122:123]
	v_pk_mul_f32 v[124:125], v[124:125], v[124:125]
	v_cvt_pk_bf16_f32 v188, v126, v127
	v_cvt_pk_bf16_f32 v189, v128, v129
	v_cvt_pk_bf16_f32 v190, v122, v123
	v_cvt_pk_bf16_f32 v191, v124, v125
	v_fma_f32 v118, v118, v133, v172
	v_fma_f32 v119, v119, v133, v173
	v_fma_f32 v120, v120, v133, v174
	v_fma_f32 v121, v121, v133, v175
	v_fma_f32 v114, v114, v133, v176
	v_fma_f32 v115, v115, v133, v177
	v_fma_f32 v116, v116, v133, v178
	v_fma_f32 v117, v117, v133, v179
	v_max_f32_e32 v118, 0, v118
	v_max_f32_e32 v119, 0, v119
	v_max_f32_e32 v120, 0, v120
	v_max_f32_e32 v121, 0, v121
	v_max_f32_e32 v114, 0, v114
	v_max_f32_e32 v115, 0, v115
	v_max_f32_e32 v116, 0, v116
	v_max_f32_e32 v117, 0, v117
	v_pk_mul_f32 v[118:119], v[118:119], v[118:119]
	v_pk_mul_f32 v[120:121], v[120:121], v[120:121]
	v_pk_mul_f32 v[114:115], v[114:115], v[114:115]
	v_pk_mul_f32 v[116:117], v[116:117], v[116:117]
	v_cvt_pk_bf16_f32 v192, v118, v119
	v_cvt_pk_bf16_f32 v193, v120, v121
	v_cvt_pk_bf16_f32 v194, v114, v115
	v_cvt_pk_bf16_f32 v195, v116, v117
	v_mov_b32_dpp v212, v188 quad_perm:[1,0,3,2] row_mask:0xf bank_mask:0xf
	v_mov_b32_dpp v213, v189 quad_perm:[1,0,3,2] row_mask:0xf bank_mask:0xf
	v_mov_b32_dpp v214, v190 quad_perm:[1,0,3,2] row_mask:0xf bank_mask:0xf
	v_mov_b32_dpp v215, v191 quad_perm:[1,0,3,2] row_mask:0xf bank_mask:0xf
	v_mov_b32_dpp v216, v192 quad_perm:[1,0,3,2] row_mask:0xf bank_mask:0xf
	v_mov_b32_dpp v217, v193 quad_perm:[1,0,3,2] row_mask:0xf bank_mask:0xf
	v_mov_b32_dpp v218, v194 quad_perm:[1,0,3,2] row_mask:0xf bank_mask:0xf
	v_mov_b32_dpp v219, v195 quad_perm:[1,0,3,2] row_mask:0xf bank_mask:0xf
	s_mov_b64 exec, s[62:63]
	v_mov_b32_e32 v188, v216
	v_mov_b32_e32 v189, v217
	v_mov_b32_e32 v190, v218
	v_mov_b32_e32 v191, v219
	s_mov_b64 exec, s[66:67]
	v_mov_b32_e32 v192, v212
	v_mov_b32_e32 v193, v213
	v_mov_b32_e32 v194, v214
	v_mov_b32_e32 v195, v215
	s_mov_b64 exec, -1
	s_add_u32 s80, s10, 0x0
	s_addc_u32 s81, s11, 0
	s_add_u32 s82, s10, 0x2000
	s_addc_u32 s83, s11, 0
	global_store_dwordx4 v131, v[188:191], s[80:81]
	global_store_dwordx4 v131, v[192:195], s[82:83]
	v_fma_f32 v110, v110, v134, v142
	v_fma_f32 v111, v111, v134, v143
	v_fma_f32 v112, v112, v134, v144
	v_fma_f32 v113, v113, v134, v145
	v_fma_f32 v106, v106, v134, v168
	v_fma_f32 v107, v107, v134, v169
	v_fma_f32 v108, v108, v134, v170
	v_fma_f32 v109, v109, v134, v171
	v_max_f32_e32 v110, 0, v110
	v_max_f32_e32 v111, 0, v111
	v_max_f32_e32 v112, 0, v112
	v_max_f32_e32 v113, 0, v113
	v_max_f32_e32 v106, 0, v106
	v_max_f32_e32 v107, 0, v107
	v_max_f32_e32 v108, 0, v108
	v_max_f32_e32 v109, 0, v109
	v_pk_mul_f32 v[110:111], v[110:111], v[110:111]
	v_pk_mul_f32 v[112:113], v[112:113], v[112:113]
	v_pk_mul_f32 v[106:107], v[106:107], v[106:107]
	v_pk_mul_f32 v[108:109], v[108:109], v[108:109]
	v_cvt_pk_bf16_f32 v188, v110, v111
	v_cvt_pk_bf16_f32 v189, v112, v113
	v_cvt_pk_bf16_f32 v190, v106, v107
	v_cvt_pk_bf16_f32 v191, v108, v109
	v_fma_f32 v102, v102, v134, v172
	v_fma_f32 v103, v103, v134, v173
	v_fma_f32 v104, v104, v134, v174
	v_fma_f32 v105, v105, v134, v175
	v_fma_f32 v98, v98, v134, v176
	v_fma_f32 v99, v99, v134, v177
	v_fma_f32 v100, v100, v134, v178
	v_fma_f32 v101, v101, v134, v179
	v_max_f32_e32 v102, 0, v102
	v_max_f32_e32 v103, 0, v103
	v_max_f32_e32 v104, 0, v104
	v_max_f32_e32 v105, 0, v105
	v_max_f32_e32 v98, 0, v98
	v_max_f32_e32 v99, 0, v99
	v_max_f32_e32 v100, 0, v100
	v_max_f32_e32 v101, 0, v101
	v_pk_mul_f32 v[102:103], v[102:103], v[102:103]
	v_pk_mul_f32 v[104:105], v[104:105], v[104:105]
	v_pk_mul_f32 v[98:99], v[98:99], v[98:99]
	v_pk_mul_f32 v[100:101], v[100:101], v[100:101]
	v_cvt_pk_bf16_f32 v192, v102, v103
	v_cvt_pk_bf16_f32 v193, v104, v105
	v_cvt_pk_bf16_f32 v194, v98, v99
	v_cvt_pk_bf16_f32 v195, v100, v101
	v_mov_b32_dpp v212, v188 quad_perm:[1,0,3,2] row_mask:0xf bank_mask:0xf
	v_mov_b32_dpp v213, v189 quad_perm:[1,0,3,2] row_mask:0xf bank_mask:0xf
	v_mov_b32_dpp v214, v190 quad_perm:[1,0,3,2] row_mask:0xf bank_mask:0xf
	v_mov_b32_dpp v215, v191 quad_perm:[1,0,3,2] row_mask:0xf bank_mask:0xf
	v_mov_b32_dpp v216, v192 quad_perm:[1,0,3,2] row_mask:0xf bank_mask:0xf
	v_mov_b32_dpp v217, v193 quad_perm:[1,0,3,2] row_mask:0xf bank_mask:0xf
	v_mov_b32_dpp v218, v194 quad_perm:[1,0,3,2] row_mask:0xf bank_mask:0xf
	v_mov_b32_dpp v219, v195 quad_perm:[1,0,3,2] row_mask:0xf bank_mask:0xf
	s_mov_b64 exec, s[62:63]
	v_mov_b32_e32 v188, v216
	v_mov_b32_e32 v189, v217
	v_mov_b32_e32 v190, v218
	v_mov_b32_e32 v191, v219
	s_mov_b64 exec, s[66:67]
	v_mov_b32_e32 v192, v212
	v_mov_b32_e32 v193, v213
	v_mov_b32_e32 v194, v214
	v_mov_b32_e32 v195, v215
	s_mov_b64 exec, -1
	s_add_u32 s80, s10, 0x20000
	s_addc_u32 s81, s11, 0
	s_add_u32 s82, s10, 0x22000
	s_addc_u32 s83, s11, 0
	global_store_dwordx4 v131, v[188:191], s[80:81]
	global_store_dwordx4 v131, v[192:195], s[82:83]
	v_fma_f32 v94, v94, v135, v142
	v_fma_f32 v95, v95, v135, v143
	v_fma_f32 v96, v96, v135, v144
	v_fma_f32 v97, v97, v135, v145
	v_fma_f32 v90, v90, v135, v168
	v_fma_f32 v91, v91, v135, v169
	v_fma_f32 v92, v92, v135, v170
	v_fma_f32 v93, v93, v135, v171
	v_max_f32_e32 v94, 0, v94
	v_max_f32_e32 v95, 0, v95
	v_max_f32_e32 v96, 0, v96
	v_max_f32_e32 v97, 0, v97
	v_max_f32_e32 v90, 0, v90
	v_max_f32_e32 v91, 0, v91
	v_max_f32_e32 v92, 0, v92
	v_max_f32_e32 v93, 0, v93
	v_pk_mul_f32 v[94:95], v[94:95], v[94:95]
	v_pk_mul_f32 v[96:97], v[96:97], v[96:97]
	v_pk_mul_f32 v[90:91], v[90:91], v[90:91]
	v_pk_mul_f32 v[92:93], v[92:93], v[92:93]
	v_cvt_pk_bf16_f32 v188, v94, v95
	v_cvt_pk_bf16_f32 v189, v96, v97
	v_cvt_pk_bf16_f32 v190, v90, v91
	v_cvt_pk_bf16_f32 v191, v92, v93
	v_fma_f32 v86, v86, v135, v172
	v_fma_f32 v87, v87, v135, v173
	v_fma_f32 v88, v88, v135, v174
	v_fma_f32 v89, v89, v135, v175
	v_fma_f32 v82, v82, v135, v176
	v_fma_f32 v83, v83, v135, v177
	v_fma_f32 v84, v84, v135, v178
	v_fma_f32 v85, v85, v135, v179
	v_max_f32_e32 v86, 0, v86
	v_max_f32_e32 v87, 0, v87
	v_max_f32_e32 v88, 0, v88
	v_max_f32_e32 v89, 0, v89
	v_max_f32_e32 v82, 0, v82
	v_max_f32_e32 v83, 0, v83
	v_max_f32_e32 v84, 0, v84
	v_max_f32_e32 v85, 0, v85
	v_pk_mul_f32 v[86:87], v[86:87], v[86:87]
	v_pk_mul_f32 v[88:89], v[88:89], v[88:89]
	v_pk_mul_f32 v[82:83], v[82:83], v[82:83]
	v_pk_mul_f32 v[84:85], v[84:85], v[84:85]
	v_cvt_pk_bf16_f32 v192, v86, v87
	v_cvt_pk_bf16_f32 v193, v88, v89
	v_cvt_pk_bf16_f32 v194, v82, v83
	v_cvt_pk_bf16_f32 v195, v84, v85
	v_mov_b32_dpp v212, v188 quad_perm:[1,0,3,2] row_mask:0xf bank_mask:0xf
	v_mov_b32_dpp v213, v189 quad_perm:[1,0,3,2] row_mask:0xf bank_mask:0xf
	v_mov_b32_dpp v214, v190 quad_perm:[1,0,3,2] row_mask:0xf bank_mask:0xf
	v_mov_b32_dpp v215, v191 quad_perm:[1,0,3,2] row_mask:0xf bank_mask:0xf
	v_mov_b32_dpp v216, v192 quad_perm:[1,0,3,2] row_mask:0xf bank_mask:0xf
	v_mov_b32_dpp v217, v193 quad_perm:[1,0,3,2] row_mask:0xf bank_mask:0xf
	v_mov_b32_dpp v218, v194 quad_perm:[1,0,3,2] row_mask:0xf bank_mask:0xf
	v_mov_b32_dpp v219, v195 quad_perm:[1,0,3,2] row_mask:0xf bank_mask:0xf
	s_mov_b64 exec, s[62:63]
	v_mov_b32_e32 v188, v216
	v_mov_b32_e32 v189, v217
	v_mov_b32_e32 v190, v218
	v_mov_b32_e32 v191, v219
	s_mov_b64 exec, s[66:67]
	v_mov_b32_e32 v192, v212
	v_mov_b32_e32 v193, v213
	v_mov_b32_e32 v194, v214
	v_mov_b32_e32 v195, v215
	s_mov_b64 exec, -1
	s_add_u32 s80, s10, 0x40000
	s_addc_u32 s81, s11, 0
	s_add_u32 s82, s10, 0x42000
	s_addc_u32 s83, s11, 0
	global_store_dwordx4 v131, v[188:191], s[80:81]
	global_store_dwordx4 v131, v[192:195], s[82:83]
	v_fma_f32 v78, v78, v136, v142
	v_fma_f32 v79, v79, v136, v143
	v_fma_f32 v80, v80, v136, v144
	v_fma_f32 v81, v81, v136, v145
	v_fma_f32 v74, v74, v136, v168
	v_fma_f32 v75, v75, v136, v169
	v_fma_f32 v76, v76, v136, v170
	v_fma_f32 v77, v77, v136, v171
	v_max_f32_e32 v78, 0, v78
	v_max_f32_e32 v79, 0, v79
	v_max_f32_e32 v80, 0, v80
	v_max_f32_e32 v81, 0, v81
	v_max_f32_e32 v74, 0, v74
	v_max_f32_e32 v75, 0, v75
	v_max_f32_e32 v76, 0, v76
	v_max_f32_e32 v77, 0, v77
	v_pk_mul_f32 v[78:79], v[78:79], v[78:79]
	v_pk_mul_f32 v[80:81], v[80:81], v[80:81]
	v_pk_mul_f32 v[74:75], v[74:75], v[74:75]
	v_pk_mul_f32 v[76:77], v[76:77], v[76:77]
	v_cvt_pk_bf16_f32 v188, v78, v79
	v_cvt_pk_bf16_f32 v189, v80, v81
	v_cvt_pk_bf16_f32 v190, v74, v75
	v_cvt_pk_bf16_f32 v191, v76, v77
	v_fma_f32 v70, v70, v136, v172
	v_fma_f32 v71, v71, v136, v173
	v_fma_f32 v72, v72, v136, v174
	v_fma_f32 v73, v73, v136, v175
	v_fma_f32 v66, v66, v136, v176
	v_fma_f32 v67, v67, v136, v177
	v_fma_f32 v68, v68, v136, v178
	v_fma_f32 v69, v69, v136, v179
	v_max_f32_e32 v70, 0, v70
	v_max_f32_e32 v71, 0, v71
	v_max_f32_e32 v72, 0, v72
	v_max_f32_e32 v73, 0, v73
	v_max_f32_e32 v66, 0, v66
	v_max_f32_e32 v67, 0, v67
	v_max_f32_e32 v68, 0, v68
	v_max_f32_e32 v69, 0, v69
	v_pk_mul_f32 v[70:71], v[70:71], v[70:71]
	v_pk_mul_f32 v[72:73], v[72:73], v[72:73]
	v_pk_mul_f32 v[66:67], v[66:67], v[66:67]
	v_pk_mul_f32 v[68:69], v[68:69], v[68:69]
	v_cvt_pk_bf16_f32 v192, v70, v71
	v_cvt_pk_bf16_f32 v193, v72, v73
	v_cvt_pk_bf16_f32 v194, v66, v67
	v_cvt_pk_bf16_f32 v195, v68, v69
	v_mov_b32_dpp v212, v188 quad_perm:[1,0,3,2] row_mask:0xf bank_mask:0xf
	v_mov_b32_dpp v213, v189 quad_perm:[1,0,3,2] row_mask:0xf bank_mask:0xf
	v_mov_b32_dpp v214, v190 quad_perm:[1,0,3,2] row_mask:0xf bank_mask:0xf
	v_mov_b32_dpp v215, v191 quad_perm:[1,0,3,2] row_mask:0xf bank_mask:0xf
	v_mov_b32_dpp v216, v192 quad_perm:[1,0,3,2] row_mask:0xf bank_mask:0xf
	v_mov_b32_dpp v217, v193 quad_perm:[1,0,3,2] row_mask:0xf bank_mask:0xf
	v_mov_b32_dpp v218, v194 quad_perm:[1,0,3,2] row_mask:0xf bank_mask:0xf
	v_mov_b32_dpp v219, v195 quad_perm:[1,0,3,2] row_mask:0xf bank_mask:0xf
	s_mov_b64 exec, s[62:63]
	v_mov_b32_e32 v188, v216
	v_mov_b32_e32 v189, v217
	v_mov_b32_e32 v190, v218
	v_mov_b32_e32 v191, v219
	s_mov_b64 exec, s[66:67]
	v_mov_b32_e32 v192, v212
	v_mov_b32_e32 v193, v213
	v_mov_b32_e32 v194, v214
	v_mov_b32_e32 v195, v215
	s_mov_b64 exec, -1
	s_add_u32 s80, s10, 0x60000
	s_addc_u32 s81, s11, 0
	s_add_u32 s82, s10, 0x62000
	s_addc_u32 s83, s11, 0
	global_store_dwordx4 v131, v[188:191], s[80:81]
	global_store_dwordx4 v131, v[192:195], s[82:83]
	v_fma_f32 v62, v62, v137, v142
	v_fma_f32 v63, v63, v137, v143
	v_fma_f32 v64, v64, v137, v144
	v_fma_f32 v65, v65, v137, v145
	v_fma_f32 v58, v58, v137, v168
	v_fma_f32 v59, v59, v137, v169
	v_fma_f32 v60, v60, v137, v170
	v_fma_f32 v61, v61, v137, v171
	v_max_f32_e32 v62, 0, v62
	v_max_f32_e32 v63, 0, v63
	v_max_f32_e32 v64, 0, v64
	v_max_f32_e32 v65, 0, v65
	v_max_f32_e32 v58, 0, v58
	v_max_f32_e32 v59, 0, v59
	v_max_f32_e32 v60, 0, v60
	v_max_f32_e32 v61, 0, v61
	v_pk_mul_f32 v[62:63], v[62:63], v[62:63]
	v_pk_mul_f32 v[64:65], v[64:65], v[64:65]
	v_pk_mul_f32 v[58:59], v[58:59], v[58:59]
	v_pk_mul_f32 v[60:61], v[60:61], v[60:61]
	v_cvt_pk_bf16_f32 v188, v62, v63
	v_cvt_pk_bf16_f32 v189, v64, v65
	v_cvt_pk_bf16_f32 v190, v58, v59
	v_cvt_pk_bf16_f32 v191, v60, v61
	v_fma_f32 v54, v54, v137, v172
	v_fma_f32 v55, v55, v137, v173
	v_fma_f32 v56, v56, v137, v174
	v_fma_f32 v57, v57, v137, v175
	v_fma_f32 v50, v50, v137, v176
	v_fma_f32 v51, v51, v137, v177
	v_fma_f32 v52, v52, v137, v178
	v_fma_f32 v53, v53, v137, v179
	v_max_f32_e32 v54, 0, v54
	v_max_f32_e32 v55, 0, v55
	v_max_f32_e32 v56, 0, v56
	v_max_f32_e32 v57, 0, v57
	v_max_f32_e32 v50, 0, v50
	v_max_f32_e32 v51, 0, v51
	v_max_f32_e32 v52, 0, v52
	v_max_f32_e32 v53, 0, v53
	v_pk_mul_f32 v[54:55], v[54:55], v[54:55]
	v_pk_mul_f32 v[56:57], v[56:57], v[56:57]
	v_pk_mul_f32 v[50:51], v[50:51], v[50:51]
	v_pk_mul_f32 v[52:53], v[52:53], v[52:53]
	v_cvt_pk_bf16_f32 v192, v54, v55
	v_cvt_pk_bf16_f32 v193, v56, v57
	v_cvt_pk_bf16_f32 v194, v50, v51
	v_cvt_pk_bf16_f32 v195, v52, v53
	v_mov_b32_dpp v212, v188 quad_perm:[1,0,3,2] row_mask:0xf bank_mask:0xf
	v_mov_b32_dpp v213, v189 quad_perm:[1,0,3,2] row_mask:0xf bank_mask:0xf
	v_mov_b32_dpp v214, v190 quad_perm:[1,0,3,2] row_mask:0xf bank_mask:0xf
	v_mov_b32_dpp v215, v191 quad_perm:[1,0,3,2] row_mask:0xf bank_mask:0xf
	v_mov_b32_dpp v216, v192 quad_perm:[1,0,3,2] row_mask:0xf bank_mask:0xf
	v_mov_b32_dpp v217, v193 quad_perm:[1,0,3,2] row_mask:0xf bank_mask:0xf
	v_mov_b32_dpp v218, v194 quad_perm:[1,0,3,2] row_mask:0xf bank_mask:0xf
	v_mov_b32_dpp v219, v195 quad_perm:[1,0,3,2] row_mask:0xf bank_mask:0xf
	s_mov_b64 exec, s[62:63]
	v_mov_b32_e32 v188, v216
	v_mov_b32_e32 v189, v217
	v_mov_b32_e32 v190, v218
	v_mov_b32_e32 v191, v219
	s_mov_b64 exec, s[66:67]
	v_mov_b32_e32 v192, v212
	v_mov_b32_e32 v193, v213
	v_mov_b32_e32 v194, v214
	v_mov_b32_e32 v195, v215
	s_mov_b64 exec, -1
	s_add_u32 s80, s10, 0x100000
	s_addc_u32 s81, s11, 0
	s_add_u32 s82, s10, 0x102000
	s_addc_u32 s83, s11, 0
	global_store_dwordx4 v131, v[188:191], s[80:81]
	global_store_dwordx4 v131, v[192:195], s[82:83]
	v_fma_f32 v46, v46, v138, v142
	v_fma_f32 v47, v47, v138, v143
	v_fma_f32 v48, v48, v138, v144
	v_fma_f32 v49, v49, v138, v145
	v_fma_f32 v42, v42, v138, v168
	v_fma_f32 v43, v43, v138, v169
	v_fma_f32 v44, v44, v138, v170
	v_fma_f32 v45, v45, v138, v171
	v_max_f32_e32 v46, 0, v46
	v_max_f32_e32 v47, 0, v47
	v_max_f32_e32 v48, 0, v48
	v_max_f32_e32 v49, 0, v49
	v_max_f32_e32 v42, 0, v42
	v_max_f32_e32 v43, 0, v43
	v_max_f32_e32 v44, 0, v44
	v_max_f32_e32 v45, 0, v45
	v_pk_mul_f32 v[46:47], v[46:47], v[46:47]
	v_pk_mul_f32 v[48:49], v[48:49], v[48:49]
	v_pk_mul_f32 v[42:43], v[42:43], v[42:43]
	v_pk_mul_f32 v[44:45], v[44:45], v[44:45]
	v_cvt_pk_bf16_f32 v188, v46, v47
	v_cvt_pk_bf16_f32 v189, v48, v49
	v_cvt_pk_bf16_f32 v190, v42, v43
	v_cvt_pk_bf16_f32 v191, v44, v45
	v_fma_f32 v38, v38, v138, v172
	v_fma_f32 v39, v39, v138, v173
	v_fma_f32 v40, v40, v138, v174
	v_fma_f32 v41, v41, v138, v175
	v_fma_f32 v34, v34, v138, v176
	v_fma_f32 v35, v35, v138, v177
	v_fma_f32 v36, v36, v138, v178
	v_fma_f32 v37, v37, v138, v179
	v_max_f32_e32 v38, 0, v38
	v_max_f32_e32 v39, 0, v39
	v_max_f32_e32 v40, 0, v40
	v_max_f32_e32 v41, 0, v41
	v_max_f32_e32 v34, 0, v34
	v_max_f32_e32 v35, 0, v35
	v_max_f32_e32 v36, 0, v36
	v_max_f32_e32 v37, 0, v37
	v_pk_mul_f32 v[38:39], v[38:39], v[38:39]
	v_pk_mul_f32 v[40:41], v[40:41], v[40:41]
	v_pk_mul_f32 v[34:35], v[34:35], v[34:35]
	v_pk_mul_f32 v[36:37], v[36:37], v[36:37]
	v_cvt_pk_bf16_f32 v192, v38, v39
	v_cvt_pk_bf16_f32 v193, v40, v41
	v_cvt_pk_bf16_f32 v194, v34, v35
	v_cvt_pk_bf16_f32 v195, v36, v37
	v_mov_b32_dpp v212, v188 quad_perm:[1,0,3,2] row_mask:0xf bank_mask:0xf
	v_mov_b32_dpp v213, v189 quad_perm:[1,0,3,2] row_mask:0xf bank_mask:0xf
	v_mov_b32_dpp v214, v190 quad_perm:[1,0,3,2] row_mask:0xf bank_mask:0xf
	v_mov_b32_dpp v215, v191 quad_perm:[1,0,3,2] row_mask:0xf bank_mask:0xf
	v_mov_b32_dpp v216, v192 quad_perm:[1,0,3,2] row_mask:0xf bank_mask:0xf
	v_mov_b32_dpp v217, v193 quad_perm:[1,0,3,2] row_mask:0xf bank_mask:0xf
	v_mov_b32_dpp v218, v194 quad_perm:[1,0,3,2] row_mask:0xf bank_mask:0xf
	v_mov_b32_dpp v219, v195 quad_perm:[1,0,3,2] row_mask:0xf bank_mask:0xf
	s_mov_b64 exec, s[62:63]
	v_mov_b32_e32 v188, v216
	v_mov_b32_e32 v189, v217
	v_mov_b32_e32 v190, v218
	v_mov_b32_e32 v191, v219
	s_mov_b64 exec, s[66:67]
	v_mov_b32_e32 v192, v212
	v_mov_b32_e32 v193, v213
	v_mov_b32_e32 v194, v214
	v_mov_b32_e32 v195, v215
	s_mov_b64 exec, -1
	s_add_u32 s80, s10, 0x120000
	s_addc_u32 s81, s11, 0
	s_add_u32 s82, s10, 0x122000
	s_addc_u32 s83, s11, 0
	global_store_dwordx4 v131, v[188:191], s[80:81]
	global_store_dwordx4 v131, v[192:195], s[82:83]
	v_fma_f32 v30, v30, v139, v142
	v_fma_f32 v31, v31, v139, v143
	v_fma_f32 v32, v32, v139, v144
	v_fma_f32 v33, v33, v139, v145
	v_fma_f32 v26, v26, v139, v168
	v_fma_f32 v27, v27, v139, v169
	v_fma_f32 v28, v28, v139, v170
	v_fma_f32 v29, v29, v139, v171
	v_max_f32_e32 v30, 0, v30
	v_max_f32_e32 v31, 0, v31
	v_max_f32_e32 v32, 0, v32
	v_max_f32_e32 v33, 0, v33
	v_max_f32_e32 v26, 0, v26
	v_max_f32_e32 v27, 0, v27
	v_max_f32_e32 v28, 0, v28
	v_max_f32_e32 v29, 0, v29
	v_pk_mul_f32 v[30:31], v[30:31], v[30:31]
	v_pk_mul_f32 v[32:33], v[32:33], v[32:33]
	v_pk_mul_f32 v[26:27], v[26:27], v[26:27]
	v_pk_mul_f32 v[28:29], v[28:29], v[28:29]
	v_cvt_pk_bf16_f32 v188, v30, v31
	v_cvt_pk_bf16_f32 v189, v32, v33
	v_cvt_pk_bf16_f32 v190, v26, v27
	v_cvt_pk_bf16_f32 v191, v28, v29
	v_fma_f32 v22, v22, v139, v172
	v_fma_f32 v23, v23, v139, v173
	v_fma_f32 v24, v24, v139, v174
	v_fma_f32 v25, v25, v139, v175
	v_fma_f32 v18, v18, v139, v176
	v_fma_f32 v19, v19, v139, v177
	v_fma_f32 v20, v20, v139, v178
	v_fma_f32 v21, v21, v139, v179
	v_max_f32_e32 v22, 0, v22
	v_max_f32_e32 v23, 0, v23
	v_max_f32_e32 v24, 0, v24
	v_max_f32_e32 v25, 0, v25
	v_max_f32_e32 v18, 0, v18
	v_max_f32_e32 v19, 0, v19
	v_max_f32_e32 v20, 0, v20
	v_max_f32_e32 v21, 0, v21
	v_pk_mul_f32 v[22:23], v[22:23], v[22:23]
	v_pk_mul_f32 v[24:25], v[24:25], v[24:25]
	v_pk_mul_f32 v[18:19], v[18:19], v[18:19]
	v_pk_mul_f32 v[20:21], v[20:21], v[20:21]
	v_cvt_pk_bf16_f32 v192, v22, v23
	v_cvt_pk_bf16_f32 v193, v24, v25
	v_cvt_pk_bf16_f32 v194, v18, v19
	v_cvt_pk_bf16_f32 v195, v20, v21
	v_mov_b32_dpp v212, v188 quad_perm:[1,0,3,2] row_mask:0xf bank_mask:0xf
	v_mov_b32_dpp v213, v189 quad_perm:[1,0,3,2] row_mask:0xf bank_mask:0xf
	v_mov_b32_dpp v214, v190 quad_perm:[1,0,3,2] row_mask:0xf bank_mask:0xf
	v_mov_b32_dpp v215, v191 quad_perm:[1,0,3,2] row_mask:0xf bank_mask:0xf
	v_mov_b32_dpp v216, v192 quad_perm:[1,0,3,2] row_mask:0xf bank_mask:0xf
	v_mov_b32_dpp v217, v193 quad_perm:[1,0,3,2] row_mask:0xf bank_mask:0xf
	v_mov_b32_dpp v218, v194 quad_perm:[1,0,3,2] row_mask:0xf bank_mask:0xf
	v_mov_b32_dpp v219, v195 quad_perm:[1,0,3,2] row_mask:0xf bank_mask:0xf
	s_mov_b64 exec, s[62:63]
	v_mov_b32_e32 v188, v216
	v_mov_b32_e32 v189, v217
	v_mov_b32_e32 v190, v218
	v_mov_b32_e32 v191, v219
	s_mov_b64 exec, s[66:67]
	v_mov_b32_e32 v192, v212
	v_mov_b32_e32 v193, v213
	v_mov_b32_e32 v194, v214
	v_mov_b32_e32 v195, v215
	s_mov_b64 exec, -1
	s_add_u32 s80, s10, 0x140000
	s_addc_u32 s81, s11, 0
	s_add_u32 s82, s10, 0x142000
	s_addc_u32 s83, s11, 0
	global_store_dwordx4 v131, v[188:191], s[80:81]
	global_store_dwordx4 v131, v[192:195], s[82:83]
	v_fma_f32 v14, v14, v140, v142
	v_fma_f32 v15, v15, v140, v143
	v_fma_f32 v16, v16, v140, v144
	v_fma_f32 v17, v17, v140, v145
	v_fma_f32 v10, v10, v140, v168
	v_fma_f32 v11, v11, v140, v169
	v_fma_f32 v12, v12, v140, v170
	v_fma_f32 v13, v13, v140, v171
	v_max_f32_e32 v14, 0, v14
	v_max_f32_e32 v15, 0, v15
	v_max_f32_e32 v16, 0, v16
	v_max_f32_e32 v17, 0, v17
	v_max_f32_e32 v10, 0, v10
	v_max_f32_e32 v11, 0, v11
	v_max_f32_e32 v12, 0, v12
	v_max_f32_e32 v13, 0, v13
	v_pk_mul_f32 v[14:15], v[14:15], v[14:15]
	v_pk_mul_f32 v[16:17], v[16:17], v[16:17]
	v_pk_mul_f32 v[10:11], v[10:11], v[10:11]
	v_pk_mul_f32 v[12:13], v[12:13], v[12:13]
	v_cvt_pk_bf16_f32 v188, v14, v15
	v_cvt_pk_bf16_f32 v189, v16, v17
	v_cvt_pk_bf16_f32 v190, v10, v11
	v_cvt_pk_bf16_f32 v191, v12, v13
	v_fma_f32 v6, v6, v140, v172
	v_fma_f32 v7, v7, v140, v173
	v_fma_f32 v8, v8, v140, v174
	v_fma_f32 v9, v9, v140, v175
	v_fma_f32 v2, v2, v140, v176
	v_fma_f32 v3, v3, v140, v177
	v_fma_f32 v4, v4, v140, v178
	v_fma_f32 v5, v5, v140, v179
	v_max_f32_e32 v6, 0, v6
	v_max_f32_e32 v7, 0, v7
	v_max_f32_e32 v8, 0, v8
	v_max_f32_e32 v9, 0, v9
	v_max_f32_e32 v2, 0, v2
	v_max_f32_e32 v3, 0, v3
	v_max_f32_e32 v4, 0, v4
	v_max_f32_e32 v5, 0, v5
	v_pk_mul_f32 v[6:7], v[6:7], v[6:7]
	v_pk_mul_f32 v[8:9], v[8:9], v[8:9]
	v_pk_mul_f32 v[2:3], v[2:3], v[2:3]
	v_pk_mul_f32 v[4:5], v[4:5], v[4:5]
	v_cvt_pk_bf16_f32 v192, v6, v7
	v_cvt_pk_bf16_f32 v193, v8, v9
	v_cvt_pk_bf16_f32 v194, v2, v3
	v_cvt_pk_bf16_f32 v195, v4, v5
	v_mov_b32_dpp v212, v188 quad_perm:[1,0,3,2] row_mask:0xf bank_mask:0xf
	v_mov_b32_dpp v213, v189 quad_perm:[1,0,3,2] row_mask:0xf bank_mask:0xf
	v_mov_b32_dpp v214, v190 quad_perm:[1,0,3,2] row_mask:0xf bank_mask:0xf
	v_mov_b32_dpp v215, v191 quad_perm:[1,0,3,2] row_mask:0xf bank_mask:0xf
	v_mov_b32_dpp v216, v192 quad_perm:[1,0,3,2] row_mask:0xf bank_mask:0xf
	v_mov_b32_dpp v217, v193 quad_perm:[1,0,3,2] row_mask:0xf bank_mask:0xf
	v_mov_b32_dpp v218, v194 quad_perm:[1,0,3,2] row_mask:0xf bank_mask:0xf
	v_mov_b32_dpp v219, v195 quad_perm:[1,0,3,2] row_mask:0xf bank_mask:0xf
	s_mov_b64 exec, s[62:63]
	v_mov_b32_e32 v188, v216
	v_mov_b32_e32 v189, v217
	v_mov_b32_e32 v190, v218
	v_mov_b32_e32 v191, v219
	s_mov_b64 exec, s[66:67]
	v_mov_b32_e32 v192, v212
	v_mov_b32_e32 v193, v213
	v_mov_b32_e32 v194, v214
	v_mov_b32_e32 v195, v215
	s_mov_b64 exec, -1
	s_add_u32 s80, s10, 0x160000
	s_addc_u32 s81, s11, 0
	s_add_u32 s82, s10, 0x162000
	s_addc_u32 s83, s11, 0
	global_store_dwordx4 v131, v[188:191], s[80:81]
	global_store_dwordx4 v131, v[192:195], s[82:83]
	s_mov_b32 s19, 0x160000
	s_lshl_b32 s21, s41, 2
	s_mov_b64 s[26:27], 0x160000
	s_andn2_b64 vcc, exec, s[12:13]
	s_mov_b64 s[12:13], -1
	s_cbranch_vccnz .LBB0_1383
	s_andn2_b64 vcc, exec, s[0:1]
	s_cbranch_vccnz .LBB0_1382
	s_barrier
	s_branch .LBB0_1382
